# stack + HALFN tile: row sum-of-squares loaded before its K-loop instead of at epilogue start
# baseline (speedup 1.0000x reference)
; template <class Epi, class Order = StaticOrder, bool HALFN = false>
; __device__ __forceinline__ void gemm_phase(LAS unsigned char* lds, const Gemm g, const Epi& E) {
;     ...
;         const char* nA = has_next ? (const char*)g.A + (size_t)nxt.pm * tstepA + (size_t)nxt.pn * g.a_pn_off * 2 : cA; const char* nB = has_next ? (const char*)g.Bt + (size_t)nxt.pn * tstepB + (HALFN ? (size_t)(nxt.half - 1) * hstepB : (size_t)0) : cB;
; #pragma unroll 1
;         for (int t = 0; t < nt; t += 2) {
;             const bool last = (t == nt - 2);
;             if constexpr (Epi::SEAMS) { if (t == Epi::SEAM0 || t == Epi::SEAM1) E.seam(acc, cur, t == Epi::SEAM0 ? 0 : 1, wr, wc, fr, fq); }
;             const char* a1 = cA + (size_t)(t + 1) * kstep;
;             const char* a2 = last ? nA : cA + (size_t)(t + 2) * kstep; const char* b2 = last ? nB : cB + (size_t)(t + 2) * kstep;
;             const char* a3 = a2 + kstep; const char* b3 = b2 + kstep;
;             PG8_LDB(B0, 0, 0); if constexpr (!HALFN) PG8_LDB(B1, 0, 1); PG8_SCHED; PG8_LDA(At, 0, 0); PG8_STAGE(PG8_SA(1, 1), a1 + hstepA, voffA);
;             PG8_WAIT_V(8); PG8_WAIT_L(0); PG8_BAR; PG8_MMA(0, 0, At, B0); if constexpr (!HALFN) PG8_MMA(0, 1, At, B1); PG8_BAR; PG8_SCHED;
;             PG8_LDA(At, 0, 1); PG8_STAGE(PG8_SB(0, 0), b2, voffB); PG8_STAGE(PG8_SB(0, 1), b2 + hstepB, voffB); PG8_STAGE(PG8_SA(0, 0), a2, voffA);
;             PG8_WAIT_V(8); PG8_WAIT_L(0); PG8_BAR; PG8_MMA(1, 0, At, B0); if constexpr (!HALFN) PG8_MMA(1, 1, At, B1); PG8_BAR; PG8_SCHED;
;             PG8_LDB(B0, 1, 0); if constexpr (!HALFN) PG8_LDB(B1, 1, 1); PG8_SCHED; PG8_LDA(At, 1, 0); PG8_STAGE(PG8_SA(0, 1), a2 + hstepA, voffA);
;             PG8_WAIT_V(8); PG8_WAIT_L(0); PG8_BAR; PG8_MMA(0, 0, At, B0); if constexpr (!HALFN) PG8_MMA(0, 1, At, B1); PG8_BAR; PG8_SCHED;
;             PG8_LDA(At, 1, 1); PG8_STAGE(PG8_SB(1, 0), b3, voffB); PG8_STAGE(PG8_SB(1, 1), b3 + hstepB, voffB); PG8_STAGE(PG8_SA(1, 0), a3, voffA);
;             PG8_WAIT_V(8); PG8_WAIT_L(0); PG8_BAR; PG8_MMA(1, 0, At, B0); if constexpr (!HALFN) PG8_MMA(1, 1, At, B1); PG8_BAR; PG8_SCHED;
;         }
;         if (wr == 0) PG8_BAR;
;         E(acc, cur, wr, wc, fr, fq);
;         if (!has_next) break;
;         if constexpr (Epi::INIT) E.init(acc, nxt, wr, wc, fr, fq);
;         else {
; #pragma unroll
;         for (int a = 0; a < 2; ++a)
; #pragma unroll
.LBB0_238:
	s_ashr_i32 s83, s82, 31
	s_lshl_b64 s[6:7], s[82:83], 20
	s_add_u32 s6, s0, s6
	s_addc_u32 s7, s1, s7
	s_and_b64 s[8:9], s[74:75], exec
	s_cselect_b32 s25, s7, s93
	s_cselect_b32 s26, s6, s92
	s_ashr_i32 s63, s62, 31
	s_lshl_b64 s[8:9], s[62:63], 20
	s_add_u32 s27, s10, s8
	s_addc_u32 s28, s11, s9
	s_ashr_i32 s55, s54, 31
	s_lshl_b64 s[8:9], s[54:55], 19
	s_add_u32 s8, s27, s8
	s_addc_u32 s9, s28, s9
	s_add_u32 s94, s8, 0xfff80000
	s_addc_u32 s95, s9, -1
	s_and_b64 s[8:9], s[74:75], exec
	s_cselect_b32 s27, s95, s5
	s_cselect_b32 s28, s94, s4
	s_add_u32 vcc_lo, s92, 0x80080
	s_addc_u32 vcc_hi, s93, 0
	s_add_u32 s29, s4, 0x100
	v_mov_b32_e32 v2, 0
	s_addc_u32 s30, s5, 0
	s_mov_b32 s31, -2
	v_mov_b32_e32 v3, v2
	v_mov_b32_e32 v4, v2
	v_mov_b32_e32 v5, v2
	v_mov_b32_e32 v6, v2
	v_mov_b32_e32 v7, v2
	v_mov_b32_e32 v8, v2
	v_mov_b32_e32 v9, v2
	v_mov_b32_e32 v10, v2
	v_mov_b32_e32 v11, v2
	v_mov_b32_e32 v12, v2
	v_mov_b32_e32 v13, v2
	v_mov_b32_e32 v14, v2
	v_mov_b32_e32 v15, v2
	v_mov_b32_e32 v16, v2
	v_mov_b32_e32 v17, v2
	v_mov_b32_e32 v18, v2
	v_mov_b32_e32 v19, v2
	v_mov_b32_e32 v20, v2
	v_mov_b32_e32 v21, v2
	v_mov_b32_e32 v22, v2
	v_mov_b32_e32 v23, v2
	v_mov_b32_e32 v24, v2
	v_mov_b32_e32 v25, v2
	v_mov_b32_e32 v26, v2
	v_mov_b32_e32 v27, v2
	v_mov_b32_e32 v28, v2
	v_mov_b32_e32 v29, v2
	v_mov_b32_e32 v30, v2
	v_mov_b32_e32 v31, v2
	v_mov_b32_e32 v32, v2
	v_mov_b32_e32 v33, v2
	v_mov_b32_e32 v34, v2
	v_mov_b32_e32 v35, v2
	v_mov_b32_e32 v36, v2
	v_mov_b32_e32 v37, v2
	v_mov_b32_e32 v38, v2
	v_mov_b32_e32 v39, v2
	v_mov_b32_e32 v40, v2
	v_mov_b32_e32 v41, v2
	v_mov_b32_e32 v42, v2
	v_mov_b32_e32 v43, v2
	v_mov_b32_e32 v44, v2
	v_mov_b32_e32 v45, v2
	v_mov_b32_e32 v46, v2
	v_mov_b32_e32 v47, v2
	v_mov_b32_e32 v48, v2
	v_mov_b32_e32 v49, v2
	v_mov_b32_e32 v50, v2
	v_mov_b32_e32 v51, v2
	v_mov_b32_e32 v52, v2
	v_mov_b32_e32 v53, v2
	v_mov_b32_e32 v54, v2
	v_mov_b32_e32 v55, v2
	v_mov_b32_e32 v56, v2
	v_mov_b32_e32 v57, v2
	v_mov_b32_e32 v58, v2
	v_mov_b32_e32 v59, v2
	v_mov_b32_e32 v60, v2
	v_mov_b32_e32 v61, v2
	v_mov_b32_e32 v62, v2
	v_mov_b32_e32 v63, v2
	v_mov_b32_e32 v64, v2
	v_mov_b32_e32 v65, v2
	s_lshl_b32 s98, s50, 8
	s_add_i32 s98, s98, s22
	v_add_u32_e32 v194, s98, v1
	v_ashrrev_i32_e32 v195, 31, v194
	v_lshl_add_u64 v[194:195], v[194:195], 2, s[44:45]
	global_load_dword v196, v[194:195], off
	global_load_dword v197, v[194:195], off offset:64
	global_load_dword v198, v[194:195], off offset:128
	global_load_dword v199, v[194:195], off offset:192
	global_load_dword v200, v[194:195], off offset:512
	global_load_dword v201, v[194:195], off offset:576
	global_load_dword v202, v[194:195], off offset:640
	global_load_dword v203, v[194:195], off offset:704

;     __device__ __forceinline__ void operator()(f32x4 (&acc)[2][2][4][2], const Unit& u, int wr, int wc, int fr, int fq) const {
;     ...
;         for (int ai = 0; ai < 2; ++ai)
; #pragma unroll
;             for (int m = 0; m < 4; ++m) rsv[ai][m] = ssq[u.pm * 256 + ai * 128 + wr * 64 + m * 16 + fr];
;         asm volatile("" ::: "memory");
; #pragma unroll
;         for (int ai = 0; ai < 2; ++ai)
; #pragma unroll
;             for (int m = 0; m < 4; ++m) rsv[ai][m] = __builtin_amdgcn_rsqf(rsv[ai][m] * (1.0f / DM) + RMS_EPS);
.LBB0_242:
	s_lshl_b32 s4, s50, 8
	v_mov_b32_e32 v78, v1
	v_mov_b32_e32 v114, v79
	s_add_i32 s4, s4, s22
	s_add_i32 s8, s52, 56
	v_add_u32_e32 v88, s4, v78
	v_ashrrev_i32_e32 v89, 31, v88
	v_add_u32_e32 v113, 16, v88
	v_add_u32_e32 v112, 32, v88
	v_add_u32_e32 v93, 48, v88
	v_add_u32_e32 v91, 0x80, v88
	v_add_u32_e32 v89, 0x90, v88
	v_add_u32_e32 v87, 0xa0, v88
	v_add_u32_e32 v85, 0xb0, v88
	s_cmpk_gt_i32 s52, 0xffcf
	s_mov_b64 s[4:5], -1
	s_waitcnt vmcnt(0)
	v_fmamk_f32 v78, v196, 0x3a000000, v189
	v_fmamk_f32 v80, v197, 0x3a000000, v189
	v_fmamk_f32 v82, v198, 0x3a000000, v189
	v_fmamk_f32 v86, v199, 0x3a000000, v189
	v_fmamk_f32 v95, v200, 0x3a000000, v189
	v_fmamk_f32 v96, v201, 0x3a000000, v189
	v_fmamk_f32 v97, v202, 0x3a000000, v189
	v_fmamk_f32 v98, v203, 0x3a000000, v189
	v_rsq_f32_e32 v94, v78
	v_rsq_f32_e32 v92, v80
	v_rsq_f32_e32 v90, v82
	v_rsq_f32_e32 v86, v86
	v_rsq_f32_e32 v84, v95
	v_rsq_f32_e32 v82, v96
	v_rsq_f32_e32 v80, v97
	v_rsq_f32_e32 v78, v98
	s_cbranch_scc1 .LBB0_245
	s_andn2_b64 vcc, exec, s[4:5]
	s_cbranch_vccz .LBB0_266

; #define SEAM(k) do { if (IN(k) && IN((k) + 1)) { if (lo < 0) grid.sync(); else xcd_barrier(xb); } } while (0)
; __device__ __forceinline__ void xcd_barrier(const XcdBarrier& b, bool local = false) {
;     asm volatile("s_waitcnt vmcnt(0)" ::: "memory");
;     __syncthreads();
;     if (threadIdx.x == 0) {
;         unsigned* bar = b.bar;
;         __builtin_amdgcn_s_waitcnt(0);
;         unsigned nloc = b.st[0], nx = b.st[1];
;         if (nloc == 0u) { xcd_barrier_complete(bar, b.x, nloc, nx); b.st[0] = nloc; b.st[1] = nx; }
; __global__ void __launch_bounds__(512, 2) fwd_megakernel(Args a) {
;     ...
;         SEAM(pb);
;         if (IN(pb + 1) && KIND(3)) {
;             if (lx >= 0) mixer_phase(a, l, lds, lx * (MTOK / TT / 8) + lr, 32, (lx + 1) * (MTOK / TT / 8));
.LBB0_270:
	v_mov_b32_e32 v194, 0x3e000000
	v_mov_b32_e32 v195, 0x3eaaaaab
	v_mov_b32_e32 v196, 0x3e800000
	v_mov_b32_e32 v197, 0x3e4ccccd
	v_mov_b32_e32 v198, 0x3e2aaaab
	v_mov_b32_e32 v199, 0x3e124925
	v_mov_b32_e32 v200, 0x3d800000
	v_mov_b32_e32 v201, 0x3de38e39
	v_mov_b32_e32 v202, 0x3dcccccd
	v_mov_b32_e32 v203, 0x3dba2e8c
	s_mul_i32 s4, s78, 6
	s_add_i32 s15, s4, 2
	s_cmp_lt_i32 s15, s97
	s_cselect_b64 s[40:41], -1, 0
	s_and_b64 s[4:5], s[42:43], s[40:41]
	s_andn2_b64 vcc, exec, s[4:5]
	s_cbranch_vccnz .LBB0_338
	v_readlane_b32 s6, v252, 54
	v_readlane_b32 s7, v252, 55
	s_mov_b64 s[4:5], -1
	s_and_b64 vcc, exec, s[6:7]
	s_cbranch_vccz .LBB0_325
	s_waitcnt vmcnt(0)
	s_waitcnt vmcnt(63) expcnt(7) lgkmcnt(15)
	s_barrier
	s_mov_b64 s[42:43], exec
	v_readlane_b32 s4, v252, 2
	v_readlane_b32 s5, v252, 3
	s_and_b64 s[4:5], s[42:43], s[4:5]
	s_mov_b64 exec, s[4:5]
	s_cbranch_execz .LBB0_324
	v_readlane_b32 s4, v251, 57
	s_waitcnt vmcnt(0) expcnt(0) lgkmcnt(0)
	s_nop 0
	v_mov_b32_e32 v1, s4
	ds_read_b32 v3, v1
	v_readlane_b32 s4, v251, 58
	s_waitcnt lgkmcnt(0)
	v_cmp_ne_u32_e32 vcc, 0, v3
	v_mov_b32_e32 v1, s4
	ds_read_b32 v2, v1
	s_cbranch_vccnz .LBB0_288
	s_mov_b32 s10, 1
	s_branch .LBB0_276
